# baseline (speedup 1.0000x reference)
; __device__ __forceinline__ float partner_sum(float v) { auto rr = __builtin_amdgcn_permlane32_swap(__float_as_uint(v), __float_as_uint(v), false, false); return __uint_as_float(rr[0]) + __uint_as_float(rr[1]); }
; __device__ __forceinline__ void df_unit_p128(ATT_LAS unsigned char* lds, const bf16_t* Q, const bf16_t* __restrict__ K, const bf16_t* __restrict__ V, bf16_t* O, int b, int h, int qb,
;                                              float lam, float post, const float* __restrict__ sub_g, const int wv) {
;     ...
;     if (mp == 0) {
;         float ss = 0.f;
; #pragma unroll
;         for (int d0 = 0; d0 < 4; ++d0)
; #pragma unroll
;             for (int i = 0; i < 4; ++i) { const f32x4 x2 = xch[(d0 * 4 + i) * 64];
; #pragma unroll
;                 for (int jj = 0; jj < 4; ++jj) { const float v = o[d0][4 * i + jj] * inv - x2[jj]; o[d0][4 * i + jj] = v; ss += v * v; } }
;         ss = partner_sum(ss);
.LBB0_233:
	s_andn2_b64 vcc, exec, s[8:9]
	s_waitcnt vmcnt(0) lgkmcnt(0)
	s_barrier
	s_cbranch_vccnz .LBB0_235
	ds_read_b128 v[6:9], v2
	ds_read_b128 v[194:197], v2 offset:1024
	ds_read_b128 v[198:201], v2 offset:2048
	ds_read_b128 v[202:205], v2 offset:3072
	s_waitcnt lgkmcnt(3)
	v_fma_f32 v37, v66, v0, -v6
	v_fma_f32 v34, v67, v0, -v7
	v_fma_f32 v35, v68, v0, -v8
	v_fma_f32 v36, v69, v0, -v9
	v_mul_f32_e32 v3, v34, v34
	v_fmac_f32_e32 v3, v37, v37
	v_fmac_f32_e32 v3, v35, v35
	v_fmac_f32_e32 v3, v36, v36
	ds_read_b128 v[6:9], v2 offset:4096
	s_waitcnt lgkmcnt(3)
	v_fma_f32 v50, v70, v0, -v194
	v_fma_f32 v51, v71, v0, -v195
	v_fma_f32 v52, v72, v0, -v196
	v_fma_f32 v53, v73, v0, -v197
	v_fmac_f32_e32 v3, v50, v50
	v_fmac_f32_e32 v3, v51, v51
	v_fmac_f32_e32 v3, v52, v52
	v_fmac_f32_e32 v3, v53, v53
	ds_read_b128 v[194:197], v2 offset:5120
	s_waitcnt lgkmcnt(3)
	v_fma_f32 v58, v74, v0, -v198
	v_fma_f32 v54, v75, v0, -v199
	v_fma_f32 v46, v76, v0, -v200
	v_fma_f32 v42, v77, v0, -v201
	v_fmac_f32_e32 v3, v58, v58
	v_fmac_f32_e32 v3, v54, v54
	v_fmac_f32_e32 v3, v46, v46
	v_fmac_f32_e32 v3, v42, v42
	ds_read_b128 v[198:201], v2 offset:6144
	s_waitcnt lgkmcnt(3)
	v_fma_f32 v71, v78, v0, -v202
	v_fma_f32 v68, v79, v0, -v203
	v_fma_f32 v65, v80, v0, -v204
	v_fma_f32 v62, v81, v0, -v205
	v_fmac_f32_e32 v3, v71, v71
	v_fmac_f32_e32 v3, v68, v68
	v_fmac_f32_e32 v3, v65, v65
	v_fmac_f32_e32 v3, v62, v62
	ds_read_b128 v[202:205], v2 offset:7168
	s_waitcnt lgkmcnt(3)
	v_fma_f32 v59, v82, v0, -v6
	v_fma_f32 v55, v83, v0, -v7
	v_fma_f32 v47, v84, v0, -v8
	v_fma_f32 v43, v85, v0, -v9
	v_fmac_f32_e32 v3, v59, v59
	v_fmac_f32_e32 v3, v55, v55
	v_fmac_f32_e32 v3, v47, v47
	v_fmac_f32_e32 v3, v43, v43
	ds_read_b128 v[6:9], v2 offset:8192
	s_waitcnt lgkmcnt(3)
	v_fma_f32 v72, v86, v0, -v194
	v_fma_f32 v69, v87, v0, -v195
	v_fma_f32 v66, v88, v0, -v196
	v_fma_f32 v63, v89, v0, -v197
	v_fmac_f32_e32 v3, v72, v72
	v_fmac_f32_e32 v3, v69, v69
	v_fmac_f32_e32 v3, v66, v66
	v_fmac_f32_e32 v3, v63, v63
	ds_read_b128 v[194:197], v2 offset:9216
	s_waitcnt lgkmcnt(3)
	v_fma_f32 v60, v90, v0, -v198
	v_fma_f32 v56, v91, v0, -v199
	v_fma_f32 v48, v92, v0, -v200
	v_fma_f32 v44, v93, v0, -v201
	v_fmac_f32_e32 v3, v60, v60
	v_fmac_f32_e32 v3, v56, v56
	v_fmac_f32_e32 v3, v48, v48
	v_fmac_f32_e32 v3, v44, v44
	ds_read_b128 v[198:201], v2 offset:10240
	s_waitcnt lgkmcnt(3)
	v_fma_f32 v73, v94, v0, -v202
	v_fma_f32 v70, v95, v0, -v203
	v_fma_f32 v67, v96, v0, -v204
	v_fma_f32 v64, v97, v0, -v205
	v_fmac_f32_e32 v3, v73, v73
	v_fmac_f32_e32 v3, v70, v70
	v_fmac_f32_e32 v3, v67, v67
	v_fmac_f32_e32 v3, v64, v64
	ds_read_b128 v[202:205], v2 offset:11264
	s_waitcnt lgkmcnt(3)
	v_fma_f32 v61, v98, v0, -v6
	v_fma_f32 v57, v99, v0, -v7
	v_fma_f32 v49, v100, v0, -v8
	v_fma_f32 v45, v101, v0, -v9
	v_fmac_f32_e32 v3, v61, v61
	v_fmac_f32_e32 v3, v57, v57
	v_fmac_f32_e32 v3, v49, v49
	v_fmac_f32_e32 v3, v45, v45
	ds_read_b128 v[6:9], v2 offset:12288
	s_waitcnt lgkmcnt(3)
	v_fma_f32 v41, v102, v0, -v194
	v_fma_f32 v40, v103, v0, -v195
	v_fma_f32 v39, v104, v0, -v196
	v_fma_f32 v38, v105, v0, -v197
	v_fmac_f32_e32 v3, v41, v41
	v_fmac_f32_e32 v3, v40, v40
	v_fmac_f32_e32 v3, v39, v39
	v_fmac_f32_e32 v3, v38, v38
	ds_read_b128 v[194:197], v2 offset:13312
	s_waitcnt lgkmcnt(3)
	v_fma_f32 v33, v106, v0, -v198
	v_fma_f32 v32, v107, v0, -v199
	v_fma_f32 v31, v108, v0, -v200
	v_fma_f32 v30, v109, v0, -v201
	v_fmac_f32_e32 v3, v33, v33
	v_fmac_f32_e32 v3, v32, v32
	v_fmac_f32_e32 v3, v31, v31
	v_fmac_f32_e32 v3, v30, v30
	ds_read_b128 v[198:201], v2 offset:14336
	s_waitcnt lgkmcnt(3)
	v_fma_f32 v29, v110, v0, -v202
	v_fma_f32 v28, v111, v0, -v203
	v_fma_f32 v27, v112, v0, -v204
	v_fma_f32 v26, v113, v0, -v205
	v_fmac_f32_e32 v3, v29, v29
	v_fmac_f32_e32 v3, v28, v28
	v_fmac_f32_e32 v3, v27, v27
	v_fmac_f32_e32 v3, v26, v26
	ds_read_b128 v[202:205], v2 offset:15360
	s_waitcnt lgkmcnt(3)
	v_fma_f32 v25, v114, v0, -v6
	v_fma_f32 v24, v115, v0, -v7
	v_fma_f32 v23, v116, v0, -v8
	v_fma_f32 v22, v117, v0, -v9
	v_fmac_f32_e32 v3, v25, v25
	v_fmac_f32_e32 v3, v24, v24
	v_fmac_f32_e32 v3, v23, v23
	v_fmac_f32_e32 v3, v22, v22
	s_waitcnt lgkmcnt(2)
	v_fma_f32 v21, v118, v0, -v194
	v_fma_f32 v20, v119, v0, -v195
	v_fma_f32 v19, v120, v0, -v196
	v_fma_f32 v18, v121, v0, -v197
	v_fmac_f32_e32 v3, v21, v21
	v_fmac_f32_e32 v3, v20, v20
	v_fmac_f32_e32 v3, v19, v19
	v_fmac_f32_e32 v3, v18, v18
	s_waitcnt lgkmcnt(1)
	v_fma_f32 v17, v122, v0, -v198
	v_fma_f32 v16, v123, v0, -v199
	v_fma_f32 v15, v124, v0, -v200
	v_fma_f32 v14, v125, v0, -v201
	v_fmac_f32_e32 v3, v17, v17
	v_fmac_f32_e32 v3, v16, v16
	v_fmac_f32_e32 v3, v15, v15
	v_fmac_f32_e32 v3, v14, v14
	s_waitcnt lgkmcnt(0)
; __device__ __forceinline__ float partner_sum(float v) { auto rr = __builtin_amdgcn_permlane32_swap(__float_as_uint(v), __float_as_uint(v), false, false); return __uint_as_float(rr[0]) + __uint_as_float(rr[1]); }
; __device__ __forceinline__ void df_unit_p128(ATT_LAS unsigned char* lds, const bf16_t* Q, const bf16_t* __restrict__ K, const bf16_t* __restrict__ V, bf16_t* O, int b, int h, int qb,
;                                              float lam, float post, const float* __restrict__ sub_g, const int wv) {
;     ...
;             for (int i = 0; i < 4; ++i) { const f32x4 x2 = xch[(d0 * 4 + i) * 64];
; #pragma unroll
;                 for (int jj = 0; jj < 4; ++jj) { const float v = o[d0][4 * i + jj] * inv - x2[jj]; o[d0][4 * i + jj] = v; ss += v * v; } }
;         ss = partner_sum(ss);
;         const float rs = __builtin_amdgcn_rsqf(ss * (1.0f / 128.0f) + 1e-6f) * post;
;         bf16_t* Ow = O + (rowbase + q0 + rg * 32 + r32e) * DM + h * 128 + 4 * hie;
; #pragma unroll
;         for (int d0 = 0; d0 < 4; ++d0)
; #pragma unroll
;             for (int i = 0; i < 4; ++i) { const f32x4 g = *(const f32x4*)(sub_g + d0 * 32 + 8 * i + 4 * hie);
	v_fma_f32 v13, v126, v0, -v202
	v_fmac_f32_e32 v3, v13, v13
	v_fma_f32 v12, v127, v0, -v203
	v_fmac_f32_e32 v3, v12, v12
	v_fma_f32 v10, v128, v0, -v204
	v_fmac_f32_e32 v3, v10, v10
	v_fma_f32 v0, v129, v0, -v205
	v_fmac_f32_e32 v3, v0, v0
	v_mov_b32_e32 v2, v3
	s_nop 1
	v_permlane32_swap_b32_e32 v3, v2
	v_add_f32_e32 v2, v3, v2
	v_fmamk_f32 v2, v2, 0x3c000000, v240
	v_rsq_f32_e32 v2, v2
	v_mov_b32_e32 v3, s27
	v_mul_f32_e32 v11, v245, v2
	v_and_or_b32 v2, v4, 31, s26
	v_ashrrev_i32_e32 v4, 3, v4
	v_lshlrev_b64 v[2:3], 11, v[2:3]
	v_and_b32_e32 v4, -4, v4
	v_lshl_add_u64 v[2:3], s[56:57], 0, v[2:3]
	v_ashrrev_i32_e32 v5, 31, v4
	v_lshl_add_u64 v[2:3], v[2:3], 0, s[54:55]
	v_lshl_add_u64 v[8:9], v[4:5], 2, s[0:1]
	v_lshl_add_u64 v[6:7], v[4:5], 1, v[2:3]
	global_load_dwordx4 v[130:133], v[8:9], off
	global_load_dwordx4 v[134:137], v[8:9], off offset:32
	global_load_dwordx4 v[138:141], v[8:9], off offset:64
	global_load_dwordx4 v[142:145], v[8:9], off offset:96
	global_load_dwordx4 v[146:149], v[8:9], off offset:128
	global_load_dwordx4 v[150:153], v[8:9], off offset:160
	global_load_dwordx4 v[154:157], v[8:9], off offset:192
	global_load_dwordx4 v[158:161], v[8:9], off offset:224
	global_load_dwordx4 v[162:165], v[8:9], off offset:256
	global_load_dwordx4 v[166:169], v[8:9], off offset:288
	global_load_dwordx4 v[170:173], v[8:9], off offset:320
	global_load_dwordx4 v[174:177], v[8:9], off offset:352
	global_load_dwordx4 v[178:181], v[8:9], off offset:384
	global_load_dwordx4 v[182:185], v[8:9], off offset:416
	global_load_dwordx4 v[186:189], v[8:9], off offset:448
	global_load_dwordx4 v[190:193], v[8:9], off offset:480
	s_nop 0
	v_mul_f32_e32 v37, v37, v11
	v_mul_f32_e32 v34, v34, v11
	v_mul_f32_e32 v33, v33, v11
	v_mul_f32_e32 v32, v32, v11
	v_mul_f32_e32 v29, v29, v11
	v_mul_f32_e32 v28, v28, v11
	v_mul_f32_e32 v25, v25, v11
	v_mul_f32_e32 v24, v24, v11
	v_mul_f32_e32 v21, v21, v11
	v_mul_f32_e32 v20, v20, v11
	v_mul_f32_e32 v17, v17, v11
	v_mul_f32_e32 v16, v16, v11
	v_mul_f32_e32 v0, v0, v11
	s_waitcnt vmcnt(0)
; __device__ __forceinline__ unsigned cvtpk(float lo, float hi) { unsigned r; asm volatile("v_cvt_pk_bf16_f32 %0, %1, %2" : "=v"(r) : "v"(lo), "v"(hi)); return r; }
; __device__ __forceinline__ void df_unit_p128(ATT_LAS unsigned char* lds, const bf16_t* Q, const bf16_t* __restrict__ K, const bf16_t* __restrict__ V, bf16_t* O, int b, int h, int qb,
;                                              float lam, float post, const float* __restrict__ sub_g, const int wv) {
;     ...
; #pragma unroll
;         for (int d0 = 0; d0 < 4; ++d0)
; #pragma unroll
;             for (int i = 0; i < 4; ++i) { const f32x4 g = *(const f32x4*)(sub_g + d0 * 32 + 8 * i + 4 * hie);
;                 u32x2 w; w.x = cvtpk(o[d0][4 * i] * rs * g[0], o[d0][4 * i + 1] * rs * g[1]); w.y = cvtpk(o[d0][4 * i + 2] * rs * g[2], o[d0][4 * i + 3] * rs * g[3]);
;                 *(u32x2*)(Ow + d0 * 32 + 8 * i) = w; }
	v_mul_f32_e32 v2, v130, v37
	v_mul_f32_e32 v3, v131, v34
	v_cvt_pk_bf16_f32 v2, v2, v3
	v_mul_f32_e32 v3, v35, v11
	v_mul_f32_e32 v3, v132, v3
	v_mul_f32_e32 v4, v36, v11
	v_mul_f32_e32 v4, v133, v4
	v_cvt_pk_bf16_f32 v3, v3, v4
	global_store_dwordx2 v[6:7], v[2:3], off
	v_mul_f32_e32 v34, v50, v11
	v_mul_f32_e32 v2, v134, v34
	v_mul_f32_e32 v34, v51, v11
	v_mul_f32_e32 v3, v135, v34
	v_cvt_pk_bf16_f32 v2, v2, v3
	v_mul_f32_e32 v3, v52, v11
	v_mul_f32_e32 v3, v136, v3
	v_mul_f32_e32 v4, v53, v11
	v_mul_f32_e32 v4, v137, v4
	v_cvt_pk_bf16_f32 v3, v3, v4
	global_store_dwordx2 v[6:7], v[2:3], off offset:16
	v_mul_f32_e32 v34, v58, v11
	v_mul_f32_e32 v2, v34, v138
	v_mul_f32_e32 v34, v54, v11
	v_mul_f32_e32 v3, v34, v139
	v_cvt_pk_bf16_f32 v2, v2, v3
	v_mul_f32_e32 v3, v46, v11
	v_mul_f32_e32 v3, v3, v140
	v_mul_f32_e32 v4, v42, v11
	v_mul_f32_e32 v4, v4, v141
	v_cvt_pk_bf16_f32 v3, v3, v4
	global_store_dwordx2 v[6:7], v[2:3], off offset:32
	v_mul_f32_e32 v34, v71, v11
	v_mul_f32_e32 v2, v34, v142
	v_mul_f32_e32 v34, v68, v11
	v_mul_f32_e32 v3, v34, v143
	v_cvt_pk_bf16_f32 v2, v2, v3
	v_mul_f32_e32 v3, v65, v11
	v_mul_f32_e32 v3, v3, v144
	v_mul_f32_e32 v4, v62, v11
	v_mul_f32_e32 v4, v4, v145
	v_cvt_pk_bf16_f32 v3, v3, v4
	global_store_dwordx2 v[6:7], v[2:3], off offset:48
	v_mul_f32_e32 v34, v59, v11
	v_mul_f32_e32 v2, v34, v146
	v_mul_f32_e32 v34, v55, v11
	v_mul_f32_e32 v3, v34, v147
	v_cvt_pk_bf16_f32 v2, v2, v3
	v_mul_f32_e32 v3, v47, v11
	v_mul_f32_e32 v3, v3, v148
	v_mul_f32_e32 v4, v43, v11
	v_mul_f32_e32 v4, v4, v149
	v_cvt_pk_bf16_f32 v3, v3, v4
	global_store_dwordx2 v[6:7], v[2:3], off offset:64
	v_mul_f32_e32 v34, v72, v11
	v_mul_f32_e32 v2, v34, v150
	v_mul_f32_e32 v34, v69, v11
	v_mul_f32_e32 v3, v34, v151
	v_cvt_pk_bf16_f32 v2, v2, v3
	v_mul_f32_e32 v3, v66, v11
	v_mul_f32_e32 v3, v3, v152
	v_mul_f32_e32 v4, v63, v11
	v_mul_f32_e32 v4, v4, v153
	v_cvt_pk_bf16_f32 v3, v3, v4
	global_store_dwordx2 v[6:7], v[2:3], off offset:80
	v_mul_f32_e32 v34, v60, v11
	v_mul_f32_e32 v2, v34, v154
	v_mul_f32_e32 v34, v56, v11
	v_mul_f32_e32 v3, v34, v155
	v_cvt_pk_bf16_f32 v2, v2, v3
	v_mul_f32_e32 v3, v48, v11
	v_mul_f32_e32 v3, v3, v156
	v_mul_f32_e32 v4, v44, v11
	v_mul_f32_e32 v4, v4, v157
	v_cvt_pk_bf16_f32 v3, v3, v4
	global_store_dwordx2 v[6:7], v[2:3], off offset:96
	v_mul_f32_e32 v34, v73, v11
	v_mul_f32_e32 v2, v34, v158
	v_mul_f32_e32 v34, v70, v11
	v_mul_f32_e32 v3, v34, v159
	v_cvt_pk_bf16_f32 v2, v2, v3
	v_mul_f32_e32 v3, v67, v11
	v_mul_f32_e32 v3, v3, v160
	v_mul_f32_e32 v4, v64, v11
	v_mul_f32_e32 v4, v4, v161
	v_cvt_pk_bf16_f32 v3, v3, v4
	global_store_dwordx2 v[6:7], v[2:3], off offset:112
	v_mul_f32_e32 v34, v61, v11
	v_mul_f32_e32 v2, v34, v162
	v_mul_f32_e32 v34, v57, v11
	v_mul_f32_e32 v3, v34, v163
	v_cvt_pk_bf16_f32 v2, v2, v3
	v_mul_f32_e32 v3, v49, v11
	v_mul_f32_e32 v3, v3, v164
	v_mul_f32_e32 v4, v45, v11
	v_mul_f32_e32 v4, v4, v165
	v_cvt_pk_bf16_f32 v3, v3, v4
	global_store_dwordx2 v[6:7], v[2:3], off offset:128
	v_mul_f32_e32 v34, v41, v11
	v_mul_f32_e32 v2, v34, v166
	v_mul_f32_e32 v34, v40, v11
	v_mul_f32_e32 v3, v34, v167
	v_cvt_pk_bf16_f32 v2, v2, v3
	v_mul_f32_e32 v3, v39, v11
	v_mul_f32_e32 v3, v3, v168
	v_mul_f32_e32 v4, v38, v11
	v_mul_f32_e32 v4, v4, v169
	v_cvt_pk_bf16_f32 v3, v3, v4
	global_store_dwordx2 v[6:7], v[2:3], off offset:144
	v_mul_f32_e32 v2, v33, v170
	v_mul_f32_e32 v3, v32, v171
	v_cvt_pk_bf16_f32 v2, v2, v3
	v_mul_f32_e32 v3, v31, v11
	v_mul_f32_e32 v3, v3, v172
	v_mul_f32_e32 v4, v30, v11
	v_mul_f32_e32 v4, v4, v173
	v_cvt_pk_bf16_f32 v3, v3, v4
	global_store_dwordx2 v[6:7], v[2:3], off offset:160
	v_mul_f32_e32 v2, v29, v174
	v_mul_f32_e32 v3, v28, v175
	v_cvt_pk_bf16_f32 v2, v2, v3
	v_mul_f32_e32 v3, v27, v11
	v_mul_f32_e32 v3, v3, v176
	v_mul_f32_e32 v4, v26, v11
	v_mul_f32_e32 v4, v4, v177
	v_cvt_pk_bf16_f32 v3, v3, v4
	global_store_dwordx2 v[6:7], v[2:3], off offset:176
	v_mul_f32_e32 v2, v25, v178
	v_mul_f32_e32 v3, v24, v179
	v_cvt_pk_bf16_f32 v2, v2, v3
	v_mul_f32_e32 v3, v23, v11
	v_mul_f32_e32 v3, v3, v180
	v_mul_f32_e32 v4, v22, v11
	v_mul_f32_e32 v4, v4, v181
	v_cvt_pk_bf16_f32 v3, v3, v4
	global_store_dwordx2 v[6:7], v[2:3], off offset:192
	v_mul_f32_e32 v2, v21, v182
	v_mul_f32_e32 v3, v20, v183
	v_cvt_pk_bf16_f32 v2, v2, v3
	v_mul_f32_e32 v3, v19, v11
	v_mul_f32_e32 v3, v3, v184
	v_mul_f32_e32 v4, v18, v11
	v_mul_f32_e32 v4, v4, v185
	v_cvt_pk_bf16_f32 v3, v3, v4
	global_store_dwordx2 v[6:7], v[2:3], off offset:208
	v_mul_f32_e32 v2, v17, v186
	v_mul_f32_e32 v3, v16, v187
	v_cvt_pk_bf16_f32 v2, v2, v3
	v_mul_f32_e32 v3, v15, v11
	v_mul_f32_e32 v3, v3, v188
	v_mul_f32_e32 v4, v14, v11
	v_mul_f32_e32 v4, v4, v189
	v_cvt_pk_bf16_f32 v3, v3, v4
	global_store_dwordx2 v[6:7], v[2:3], off offset:224
	v_mul_f32_e32 v8, v13, v11
	v_mul_f32_e32 v2, v8, v190
	v_mul_f32_e32 v8, v12, v11
	v_mul_f32_e32 v3, v8, v191
	v_cvt_pk_bf16_f32 v2, v2, v3
	v_mul_f32_e32 v3, v10, v11
	v_mul_f32_e32 v3, v3, v192
	v_mul_f32_e32 v0, v0, v193
	v_cvt_pk_bf16_f32 v3, v3, v0
	global_store_dwordx2 v[6:7], v[2:3], off offset:240
